# RWKV scan chunk 8-byte aligned (4-byte instructions only in adjacent pairs, .p2alignl at the chunk head); 384 conversion tiles moved from the retention workgroups' tail to the RWKV workgroups' tail
# baseline (speedup 1.0000x reference)
; __device__ __forceinline__ int fresh_tid(int wv) { int l; asm volatile("v_mbcnt_lo_u32_b32 %0, -1, 0\n\tv_mbcnt_hi_u32_b32 %0, -1, %0" : "=v"(l)); return wv * 64 + l; }
; #define LAS __attribute__((address_space(3)))
; __device__ __forceinline__ TDesc tconv_desc(const float* wg, const float* wu, const float* wd, const float* win, const float* wout, unsigned char* ws, int i) {
;     TDesc d; int mode = 0, tile = i;
;     if (i < 704) { d.W = wg; d.Bt = (bf16_t*)(ws + WS_WGU); d.K = 1024; d.N = DFF; mode = 1; }
;     else if (i < 1408) { d.W = wu; d.Bt = (bf16_t*)(ws + WS_WGU); d.K = 1024; d.N = DFF; mode = 2; tile = i - 704; }
;     else if (i < 2112) { d.W = wd; d.Bt = (bf16_t*)(ws + WS_WD); d.K = DFF; d.N = 1024; tile = i - 1408; }
;     else if (i < 3072) { d.W = win; d.Bt = (bf16_t*)(ws + WS_WIN); d.K = 1024; d.N = NCOLS; tile = i - 2112; }
;     else { d.W = wout; d.Bt = (bf16_t*)(ws + WS_WOUT); d.K = 1024; d.N = 1024; tile = i - 3072; }
;     const int nkt = d.K / 64; const int kt = tile % nkt, nt = tile / nkt; d.k0 = kt * 64; d.n0 = nt * 64;
;     d.brow0 = mode == 0 ? d.n0 : ((d.n0 >> 7) * 256 + (d.n0 & 127) + (mode == 2 ? 128 : 0));
;     return d;
; }
; __device__ __forceinline__ void tconv_list(const float* wg, const float* wu, const float* wd, const float* win, const float* wout, unsigned char* ws, const int ntiles, LAS float* t, const int wv) {
;     const int tid = fresh_tid(wv); const int G = gridDim.x;
;     float cur[8], nxt[8];
;     int i = blockIdx.x;
;     if (i < ntiles) { const TDesc d = tconv_desc(wg, wu, wd, win, wout, ws, i);
; #pragma unroll
;         for (int e = 0; e < 8; ++e) { const int idx = e * 512 + tid, r = idx >> 6, c = idx & 63; cur[e] = __builtin_nontemporal_load(d.W + (size_t)(d.k0 + r) * d.N + d.n0 + c); } }
;     for (; i < ntiles; i += G) {
;         const TDesc d = tconv_desc(wg, wu, wd, win, wout, ws, i);
;         { const TDesc dn = tconv_desc(wg, wu, wd, win, wout, ws, i + G < ntiles ? i + G : i);
; #pragma unroll
;             for (int e = 0; e < 8; ++e) { const int idx = e * 512 + tid, r = idx >> 6, c = idx & 63; nxt[e] = __builtin_nontemporal_load(dn.W + (size_t)(dn.k0 + r) * dn.N + dn.n0 + c); } }
.LBB0_689:
	s_cmp_lt_u32 s2, 128
	s_cbranch_scc1 .Ltc2_skip
	v_writelane_b32 v40, s4, 4
	v_writelane_b32 v40, s5, 5
	v_writelane_b32 v40, s6, 6
	v_writelane_b32 v40, s7, 7
	v_writelane_b32 v40, s8, 8
	v_writelane_b32 v40, s9, 9
	v_writelane_b32 v40, s10, 10
	v_writelane_b32 v40, s11, 11
	v_writelane_b32 v40, s12, 12
	v_writelane_b32 v40, s13, 13
	v_writelane_b32 v40, s14, 14
	v_writelane_b32 v40, s15, 15
	v_writelane_b32 v40, s16, 16
	v_writelane_b32 v40, s17, 17
	v_writelane_b32 v40, s18, 18
	v_writelane_b32 v40, s19, 19
	v_writelane_b32 v40, s20, 20
	v_writelane_b32 v40, s21, 21
	v_writelane_b32 v40, s22, 22
	v_writelane_b32 v40, s23, 23
	v_writelane_b32 v40, s24, 24
	v_writelane_b32 v40, s25, 25
	v_writelane_b32 v40, s26, 26
	v_writelane_b32 v40, s27, 27
	v_writelane_b32 v40, s28, 28
	v_writelane_b32 v40, s29, 29
	v_writelane_b32 v40, s30, 30
	v_writelane_b32 v40, s31, 31
	s_load_dwordx2 s[24:25], s[38:39], 0xd8
	s_load_dwordx2 s[26:27], s[38:39], 0xd0
	s_load_dwordx2 s[18:19], s[38:39], 0xb8
	s_load_dwordx2 s[20:21], s[38:39], 0xc0
	s_load_dwordx2 s[22:23], s[38:39], 0xc8
	v_mbcnt_lo_u32_b32 v0, -1, 0
	v_mbcnt_hi_u32_b32 v0, -1, v0
	s_lshr_b32 s28, s33, 6
	v_lshlrev_b32_e32 v1, 2, v0
	v_lshrrev_b32_e32 v2, 5, v0
	v_and_b32_e32 v3, 31, v0
	s_mul_i32 s7, s28, 260
	v_add_u32_e32 v5, s7, v1
	v_mul_u32_u24_e32 v6, 0x208, v3
	s_lshl_b32 s7, s28, 3
	v_lshl_add_u32 v6, v2, 2, v6
	v_add_u32_e32 v6, s7, v6
	v_lshlrev_b32_e32 v3, 2, v3
	s_sub_u32 s4, s2, 128
	s_add_u32 s4, s4, 1192
	s_waitcnt lgkmcnt(0)
	s_cmp_lt_u32 s4, 704
	s_cbranch_scc0 .Ltc2_seg1_0
	s_mov_b32 s7, s4
	s_and_b32 s8, s7, 15
	s_lshr_b32 s9, s7, 4
	s_mul_i32 s7, s8, 720896
	s_lshl_b32 s29, s9, 8
	s_add_u32 s7, s7, s29
	s_mul_i32 s29, s28, 11264
	s_add_u32 s7, s7, s29
	s_add_u32 s10, s18, s7
	s_addc_u32 s11, s19, 0
	s_lshr_b32 s7, s9, 1
	s_lshl_b32 s7, s7, 8
	s_and_b32 s29, s9, 1
	s_lshl_b32 s29, s29, 6
	s_add_u32 s7, s7, s29
	s_mul_i32 s7, s7, 2048
	s_lshl_b32 s29, s8, 7
	s_add_u32 s7, s7, s29
	s_mul_i32 s29, s28, 4096
	s_add_u32 s7, s7, s29
	s_add_u32 s12, s26, 0x2100000
	s_addc_u32 s13, s27, 0
	s_add_u32 s12, s12, s7
	s_addc_u32 s13, s13, 0
	s_mov_b32 s14, 90112
	s_mov_b32 s15, 32768
	s_movk_i32 s16, 2048
	s_branch .Ltc2_segend_0

; __device__ __forceinline__ int fresh_tid(int wv) { int l; asm volatile("v_mbcnt_lo_u32_b32 %0, -1, 0\n\tv_mbcnt_hi_u32_b32 %0, -1, %0" : "=v"(l)); return wv * 64 + l; }
; #define LAS __attribute__((address_space(3)))
; __device__ __forceinline__ TDesc tconv_desc(const float* wg, const float* wu, const float* wd, const float* win, const float* wout, unsigned char* ws, int i) {
;     TDesc d; int mode = 0, tile = i;
;     if (i < 704) { d.W = wg; d.Bt = (bf16_t*)(ws + WS_WGU); d.K = 1024; d.N = DFF; mode = 1; }
;     else if (i < 1408) { d.W = wu; d.Bt = (bf16_t*)(ws + WS_WGU); d.K = 1024; d.N = DFF; mode = 2; tile = i - 704; }
;     else if (i < 2112) { d.W = wd; d.Bt = (bf16_t*)(ws + WS_WD); d.K = DFF; d.N = 1024; tile = i - 1408; }
;     else if (i < 3072) { d.W = win; d.Bt = (bf16_t*)(ws + WS_WIN); d.K = 1024; d.N = NCOLS; tile = i - 2112; }
;     else { d.W = wout; d.Bt = (bf16_t*)(ws + WS_WOUT); d.K = 1024; d.N = 1024; tile = i - 3072; }
;     const int nkt = d.K / 64; const int kt = tile % nkt, nt = tile / nkt; d.k0 = kt * 64; d.n0 = nt * 64;
;     d.brow0 = mode == 0 ? d.n0 : ((d.n0 >> 7) * 256 + (d.n0 & 127) + (mode == 2 ? 128 : 0));
;     return d;
; }
; __device__ __forceinline__ void tconv_list(const float* wg, const float* wu, const float* wd, const float* win, const float* wout, unsigned char* ws, const int ntiles, LAS float* t, const int wv) {
;     const int tid = fresh_tid(wv); const int G = gridDim.x;
;     float cur[8], nxt[8];
;     int i = blockIdx.x;
;     if (i < ntiles) { const TDesc d = tconv_desc(wg, wu, wd, win, wout, ws, i);
; #pragma unroll
;         for (int e = 0; e < 8; ++e) { const int idx = e * 512 + tid, r = idx >> 6, c = idx & 63; cur[e] = __builtin_nontemporal_load(d.W + (size_t)(d.k0 + r) * d.N + d.n0 + c); } }
;     for (; i < ntiles; i += G) {
;         const TDesc d = tconv_desc(wg, wu, wd, win, wout, ws, i);
;         { const TDesc dn = tconv_desc(wg, wu, wd, win, wout, ws, i + G < ntiles ? i + G : i);
; #pragma unroll
;             for (int e = 0; e < 8; ++e) { const int idx = e * 512 + tid, r = idx >> 6, c = idx & 63; nxt[e] = __builtin_nontemporal_load(dn.W + (size_t)(dn.k0 + r) * dn.N + dn.n0 + c); } }
.LBB0_725:
	s_or_b64 exec, exec, s[10:11]
	s_mov_b64 s[38:39], s[0:1]
	s_cmp_lt_u32 s2, 0
	s_cbranch_scc1 .Ltc7_skip
	v_writelane_b32 v40, s4, 4
	v_writelane_b32 v40, s5, 5
	v_writelane_b32 v40, s6, 6
	v_writelane_b32 v40, s7, 7
	v_writelane_b32 v40, s8, 8
	v_writelane_b32 v40, s9, 9
	v_writelane_b32 v40, s10, 10
	v_writelane_b32 v40, s11, 11
	v_writelane_b32 v40, s12, 12
	v_writelane_b32 v40, s13, 13
	v_writelane_b32 v40, s14, 14
	v_writelane_b32 v40, s15, 15
	v_writelane_b32 v40, s16, 16
	v_writelane_b32 v40, s17, 17
	v_writelane_b32 v40, s18, 18
	v_writelane_b32 v40, s19, 19
	v_writelane_b32 v40, s20, 20
	v_writelane_b32 v40, s21, 21
	v_writelane_b32 v40, s22, 22
	v_writelane_b32 v40, s23, 23
	v_writelane_b32 v40, s24, 24
	v_writelane_b32 v40, s25, 25
	v_writelane_b32 v40, s26, 26
	v_writelane_b32 v40, s27, 27
	v_writelane_b32 v40, s28, 28
	v_writelane_b32 v40, s29, 29
	v_writelane_b32 v40, s30, 30
	v_writelane_b32 v40, s31, 31
	s_load_dwordx2 s[24:25], s[38:39], 0xd8
	s_load_dwordx2 s[26:27], s[38:39], 0xd0
	s_load_dwordx2 s[18:19], s[38:39], 0xb8
	s_load_dwordx2 s[20:21], s[38:39], 0xc0
	s_load_dwordx2 s[22:23], s[38:39], 0xc8
	v_mbcnt_lo_u32_b32 v0, -1, 0
	v_mbcnt_hi_u32_b32 v0, -1, v0
	s_lshr_b32 s28, s33, 6
	v_lshlrev_b32_e32 v1, 2, v0
	v_lshrrev_b32_e32 v2, 5, v0
	v_and_b32_e32 v3, 31, v0
	s_mul_i32 s7, s28, 260
	v_add_u32_e32 v5, s7, v1
	v_mul_u32_u24_e32 v6, 0x208, v3
	s_lshl_b32 s7, s28, 3
	v_lshl_add_u32 v6, v2, 2, v6
	v_add_u32_e32 v6, s7, v6
	v_lshlrev_b32_e32 v3, 2, v3
	s_sub_u32 s4, s2, 0
	s_add_u32 s4, s4, 808
	s_waitcnt lgkmcnt(0)
	s_cmp_lt_u32 s4, 704
	s_cbranch_scc0 .Ltc7_seg1_0
	s_mov_b32 s7, s4
	s_and_b32 s8, s7, 15
	s_lshr_b32 s9, s7, 4
	s_mul_i32 s7, s8, 720896
	s_lshl_b32 s29, s9, 8
	s_add_u32 s7, s7, s29
	s_mul_i32 s29, s28, 11264
	s_add_u32 s7, s7, s29
	s_add_u32 s10, s18, s7
	s_addc_u32 s11, s19, 0
	s_lshr_b32 s7, s9, 1
	s_lshl_b32 s7, s7, 8
	s_and_b32 s29, s9, 1
	s_lshl_b32 s29, s29, 6
	s_add_u32 s7, s7, s29
	s_mul_i32 s7, s7, 2048
	s_lshl_b32 s29, s8, 7
	s_add_u32 s7, s7, s29
	s_mul_i32 s29, s28, 4096
	s_add_u32 s7, s7, s29
	s_add_u32 s12, s26, 0x2100000
	s_addc_u32 s13, s27, 0
	s_add_u32 s12, s12, s7
	s_addc_u32 s13, s13, 0
	s_mov_b32 s14, 90112
	s_mov_b32 s15, 32768
	s_movk_i32 s16, 2048
	s_branch .Ltc7_segend_0

; __device__ __forceinline__ int fresh_tid(int wv) { int l; asm volatile("v_mbcnt_lo_u32_b32 %0, -1, 0\n\tv_mbcnt_hi_u32_b32 %0, -1, %0" : "=v"(l)); return wv * 64 + l; }
; #define LAS __attribute__((address_space(3)))
; __device__ __forceinline__ TDesc tconv_desc(const float* wg, const float* wu, const float* wd, const float* win, const float* wout, unsigned char* ws, int i) {
;     TDesc d; int mode = 0, tile = i;
;     if (i < 704) { d.W = wg; d.Bt = (bf16_t*)(ws + WS_WGU); d.K = 1024; d.N = DFF; mode = 1; }
;     else if (i < 1408) { d.W = wu; d.Bt = (bf16_t*)(ws + WS_WGU); d.K = 1024; d.N = DFF; mode = 2; tile = i - 704; }
;     else if (i < 2112) { d.W = wd; d.Bt = (bf16_t*)(ws + WS_WD); d.K = DFF; d.N = 1024; tile = i - 1408; }
;     else if (i < 3072) { d.W = win; d.Bt = (bf16_t*)(ws + WS_WIN); d.K = 1024; d.N = NCOLS; tile = i - 2112; }
;     else { d.W = wout; d.Bt = (bf16_t*)(ws + WS_WOUT); d.K = 1024; d.N = 1024; tile = i - 3072; }
;     const int nkt = d.K / 64; const int kt = tile % nkt, nt = tile / nkt; d.k0 = kt * 64; d.n0 = nt * 64;
;     d.brow0 = mode == 0 ? d.n0 : ((d.n0 >> 7) * 256 + (d.n0 & 127) + (mode == 2 ? 128 : 0));
;     return d;
; }
; __device__ __forceinline__ void tconv_list(const float* wg, const float* wu, const float* wd, const float* win, const float* wout, unsigned char* ws, const int ntiles, LAS float* t, const int wv) {
;     const int tid = fresh_tid(wv); const int G = gridDim.x;
;     float cur[8], nxt[8];
;     int i = blockIdx.x;
;     if (i < ntiles) { const TDesc d = tconv_desc(wg, wu, wd, win, wout, ws, i);
; #pragma unroll
;         for (int e = 0; e < 8; ++e) { const int idx = e * 512 + tid, r = idx >> 6, c = idx & 63; cur[e] = __builtin_nontemporal_load(d.W + (size_t)(d.k0 + r) * d.N + d.n0 + c); } }
;     for (; i < ntiles; i += G) {
;         const TDesc d = tconv_desc(wg, wu, wd, win, wout, ws, i);
;         { const TDesc dn = tconv_desc(wg, wu, wd, win, wout, ws, i + G < ntiles ? i + G : i);
; #pragma unroll
;             for (int e = 0; e < 8; ++e) { const int idx = e * 512 + tid, r = idx >> 6, c = idx & 63; nxt[e] = __builtin_nontemporal_load(dn.W + (size_t)(dn.k0 + r) * dn.N + dn.n0 + c); } }
.Ltc7_loop:
	s_add_u32 s4, s4, 128
	s_cmp_lt_u32 s4, 1192
	s_cselect_b32 s31, 1, 0
	s_cbranch_scc0 .Ltc7_nonexta
	v_writelane_b32 v40, s8, 32
	v_writelane_b32 v40, s9, 33
	s_cmp_lt_u32 s4, 704
	s_cbranch_scc0 .Ltc7_seg1_1
	s_mov_b32 s7, s4
	s_and_b32 s8, s7, 15
	s_lshr_b32 s9, s7, 4
	s_mul_i32 s7, s8, 720896
	s_lshl_b32 s29, s9, 8
	s_add_u32 s7, s7, s29
	s_mul_i32 s29, s28, 11264
	s_add_u32 s7, s7, s29
	s_add_u32 s10, s18, s7
	s_addc_u32 s11, s19, 0
	s_lshr_b32 s7, s9, 1
	s_lshl_b32 s7, s7, 8
	s_and_b32 s29, s9, 1
	s_lshl_b32 s29, s29, 6
	s_add_u32 s7, s7, s29
	s_mul_i32 s7, s7, 2048
	s_lshl_b32 s29, s8, 7
	s_add_u32 s7, s7, s29
	s_mul_i32 s29, s28, 4096
	s_add_u32 s7, s7, s29
	s_add_u32 s12, s26, 0x2100000
	s_addc_u32 s13, s27, 0
	s_add_u32 s12, s12, s7
	s_addc_u32 s13, s13, 0
	s_mov_b32 s14, 90112
	s_mov_b32 s15, 32768
	s_movk_i32 s16, 2048
	s_branch .Ltc7_segend_1

; __device__ __forceinline__ unsigned cvt_pk_bf16(float lo, float hi) { const f32x2_t v = {lo, hi}; const bf16x2_t b = __builtin_convertvector(v, bf16x2_t); return __builtin_bit_cast(unsigned, b); }
; __device__ __forceinline__ void tconv_list(const float* wg, const float* wu, const float* wd, const float* win, const float* wout, unsigned char* ws, const int ntiles, LAS float* t, const int wv) {
;     ...
;         for (int e = 0; e < 8; ++e) { const int idx = e * 512 + tid, r = idx >> 6, c = idx & 63; t[r * 65 + c] = cur[e]; }
;         __syncthreads();
; #pragma unroll
;         for (int e = 0; e < 4; ++e) { const int idx = e * 512 + tid, n = idx >> 5, kp = idx & 31;
;             const unsigned w = pg8::cvt_pk_bf16(t[(2 * kp) * 65 + n], t[(2 * kp + 1) * 65 + n]);
;             *(unsigned*)(d.Bt + (size_t)(d.brow0 + n) * d.K + d.k0 + 2 * kp) = w; }
;         __syncthreads();
; #pragma unroll
;         for (int e = 0; e < 8; ++e) cur[e] = nxt[e];
;     }
.Ltc7_havea:
	ds_write_b32 v5, v8 offset:0
	ds_write_b32 v5, v9 offset:2080
	ds_write_b32 v5, v10 offset:4160
	ds_write_b32 v5, v11 offset:6240
	ds_write_b32 v5, v12 offset:8320
	ds_write_b32 v5, v13 offset:10400
	ds_write_b32 v5, v14 offset:12480
	ds_write_b32 v5, v15 offset:14560
	v_mad_u32_u24 v4, v2, s30, v3
	s_waitcnt lgkmcnt(0)
	s_barrier
	ds_read2_b32 v[24:25], v6 offset0:0 offset1:65
	ds_read2_b32 v[26:27], v6 offset0:16 offset1:81
	ds_read2_b32 v[28:29], v6 offset0:32 offset1:97
	ds_read2_b32 v[30:31], v6 offset0:48 offset1:113
	s_waitcnt lgkmcnt(3)
	v_cvt_pk_bf16_f32 v32, v24, v25
	s_waitcnt lgkmcnt(2)
	v_cvt_pk_bf16_f32 v33, v26, v27
	s_waitcnt lgkmcnt(1)
	v_cvt_pk_bf16_f32 v34, v28, v29
	s_waitcnt lgkmcnt(0)
	v_cvt_pk_bf16_f32 v35, v30, v31
	global_store_dword v4, v32, s[8:9]
	s_add_u32 s8, s8, s17
	s_addc_u32 s9, s9, 0
	global_store_dword v4, v33, s[8:9]
	s_add_u32 s8, s8, s17
	s_addc_u32 s9, s9, 0
	global_store_dword v4, v34, s[8:9]
	s_add_u32 s8, s8, s17
	s_addc_u32 s9, s9, 0
	global_store_dword v4, v35, s[8:9]
	s_barrier
	s_cmp_eq_u32 s31, 0
	s_cbranch_scc1 .Ltc7_done
	s_mov_b32 s17, s15
	s_mov_b32 s30, s16
	s_mov_b64 s[8:9], s[12:13]
	s_add_u32 s4, s4, 128
	s_cmp_lt_u32 s4, 1192
	s_cselect_b32 s31, 1, 0
	s_cbranch_scc0 .Ltc7_nonextb
	v_writelane_b32 v40, s8, 32
	v_writelane_b32 v40, s9, 33
	s_cmp_lt_u32 s4, 704
	s_cbranch_scc0 .Ltc7_seg1_2
	s_mov_b32 s7, s4
	s_and_b32 s8, s7, 15
	s_lshr_b32 s9, s7, 4
	s_mul_i32 s7, s8, 720896
	s_lshl_b32 s29, s9, 8
	s_add_u32 s7, s7, s29
	s_mul_i32 s29, s28, 11264
	s_add_u32 s7, s7, s29
	s_add_u32 s10, s18, s7
	s_addc_u32 s11, s19, 0
	s_lshr_b32 s7, s9, 1
	s_lshl_b32 s7, s7, 8
	s_and_b32 s29, s9, 1
	s_lshl_b32 s29, s29, 6
	s_add_u32 s7, s7, s29
	s_mul_i32 s7, s7, 2048
	s_lshl_b32 s29, s8, 7
	s_add_u32 s7, s7, s29
	s_mul_i32 s29, s28, 4096
	s_add_u32 s7, s7, s29
	s_add_u32 s12, s26, 0x2100000
	s_addc_u32 s13, s27, 0
	s_add_u32 s12, s12, s7
	s_addc_u32 s13, s13, 0
	s_mov_b32 s14, 90112
	s_mov_b32 s15, 32768
	s_movk_i32 s16, 2048
	s_branch .Ltc7_segend_2

; __device__ __forceinline__ int fresh_tid(int wv) { int l; asm volatile("v_mbcnt_lo_u32_b32 %0, -1, 0\n\tv_mbcnt_hi_u32_b32 %0, -1, %0" : "=v"(l)); return wv * 64 + l; }
; #define LAS __attribute__((address_space(3)))
; __device__ __forceinline__ unsigned xb_xcc_id() { return (unsigned)__builtin_amdgcn_s_getreg((3 << 11) | 20) & 0xFu; }
; #define GSYNC() do { for (int r_ = 0; r_ < REP_SYNC; ++r_) xcd_barrier((unsigned*)ws, (volatile LAS unsigned*)(lds + LDS_BYTES - 16), wv); FRESH(); } while (0)
; __device__ __forceinline__ void xcd_barrier(unsigned* barw, volatile LAS unsigned* stw, const int wv) {
;     XcdBarrier b; b.bar = barw; b.x = xb_xcc_id(); b.st = stw;
;     asm volatile("s_waitcnt vmcnt(0)" ::: "memory");
;     __syncthreads();
;     if (fresh_tid(wv) == 0) {
;         unsigned* bar = b.bar;
;         __builtin_amdgcn_s_waitcnt(0);
;         unsigned nloc = b.st[0], nx = b.st[1];
;         if (nloc == 0u) { xcd_barrier_complete(bar, b.x, nloc, nx); b.st[0] = nloc; b.st[1] = nx; }
; __global__ void __launch_bounds__(512, 2) hymba_mega(Params P_unused) {
;     ...
;     GSYNC();
.Ltc7_skip:
.LBB0_726:
	s_getreg_b32 s4, hwreg(HW_REG_XCC_ID, 0, 4)
	s_waitcnt vmcnt(0)
	s_barrier
	s_waitcnt vmcnt(4)
	v_mbcnt_lo_u32_b32 v0, -1, 0
	v_mbcnt_hi_u32_b32 v0, -1, v0
	s_nop 0
	v_cmp_eq_u32_e32 vcc, s74, v0
	s_and_saveexec_b64 s[0:1], vcc
	s_cbranch_execz .LBB0_769
	s_load_dwordx2 s[10:11], s[38:39], 0xd8
	s_waitcnt vmcnt(0) expcnt(0) lgkmcnt(0)
	s_add_u32 s8, s10, 0x200
	s_addc_u32 s9, s11, 0
	s_add_i32 s5, 0, 0x23ff0
	v_mov_b32_e32 v0, s5
	ds_read_b32 v2, v0
	s_add_i32 s5, 0, 0x23ff4
	v_mov_b32_e32 v0, s5
	ds_read_b32 v0, v0
	s_and_b32 s4, s4, 15
	s_waitcnt lgkmcnt(1)
	v_cmp_ne_u32_e32 vcc, 0, v2
	s_cbranch_vccnz .LBB0_740
	s_add_u32 s12, s10, 0x1000
	s_addc_u32 s13, s11, 0
	s_add_u32 s14, s10, 0x1100
	s_addc_u32 s15, s11, 0
	s_add_u32 s16, s10, 0x1200
	s_addc_u32 s17, s11, 0
	s_add_u32 s18, s10, 0x1300
	s_addc_u32 s19, s11, 0
	s_mov_b32 s5, 1
	v_mov_b32_e32 v16, 0
	s_branch .LBB0_730
